# v50 plus: gate stage vmcnt counted to leave previous unit stores in flight, resnorm/gate/pool/sgemm loop heads aligned
# baseline (speedup 1.0000x reference)
.LBB0_63:
	v_lshrrev_b32_e32 v0, 8, v57
	v_mul_i32_i24_e32 v0, 6, v0
	v_ashrrev_i32_e32 v1, 31, v0
	v_lshlrev_b64 v[0:1], 12, v[0:1]
	v_lshl_add_u64 v[0:1], s[8:9], 0, v[0:1]
	v_lshl_add_u64 v[2:3], v[0:1], 0, s[12:13]
	v_lshl_add_u64 v[4:5], v[2:3], 0, v[16:17]
	v_lshl_add_u64 v[2:3], v[2:3], 0, v[32:33]
	v_lshl_add_u64 v[34:35], v[0:1], 0, v[16:17]
	global_load_dwordx4 v[38:41], v[4:5], off
	global_load_dwordx4 v[42:45], v[4:5], off offset:16
	global_load_dwordx4 v[46:49], v[2:3], off
	global_load_dwordx4 v[50:53], v[2:3], off offset:16
	global_load_dwordx4 v[66:69], v[18:19], off
	global_load_dwordx4 v[70:73], v[18:19], off offset:16
	global_load_dwordx4 v[74:77], v[18:19], off offset:2064
	global_load_dwordx4 v[78:81], v[18:19], off offset:2048
	s_nop 0
	global_load_dwordx4 v[0:3], v[34:35], off
	global_load_dwordx4 v[4:7], v[34:35], off offset:16
	global_load_dwordx4 v[8:11], v[34:35], off offset:2048
	global_load_dwordx4 v[12:15], v[34:35], off offset:2064
	v_ashrrev_i32_e32 v29, 31, v28
	v_lshlrev_b64 v[34:35], 11, v[28:29]
	v_lshlrev_b64 v[36:37], 12, v[28:29]
	s_mov_b64 s[16:17], 0
	v_lshl_add_u64 v[34:35], v[20:21], 0, v[34:35]
	v_lshl_add_u64 v[36:37], v[30:31], 0, v[36:37]
	s_waitcnt vmcnt(9)
	v_pk_add_f32 v[48:49], v[48:49], 1.0 op_sel_hi:[1,0]
	v_pk_add_f32 v[84:85], v[46:47], 1.0 op_sel_hi:[1,0]
	s_waitcnt vmcnt(8)
	v_pk_add_f32 v[52:53], v[52:53], 1.0 op_sel_hi:[1,0]
	v_pk_add_f32 v[40:41], v[40:41], 1.0 op_sel_hi:[1,0]
	v_pk_add_f32 v[54:55], v[38:39], 1.0 op_sel_hi:[1,0]
	v_pk_add_f32 v[44:45], v[44:45], 1.0 op_sel_hi:[1,0]
	v_pk_add_f32 v[82:83], v[42:43], 1.0 op_sel_hi:[1,0]
	v_pk_add_f32 v[86:87], v[50:51], 1.0 op_sel_hi:[1,0]
	s_waitcnt vmcnt(7)
	v_pk_mul_f32 v[38:39], v[68:69], v[40:41]
	v_pk_mul_f32 v[40:41], v[66:67], v[54:55]
	s_waitcnt vmcnt(6)
	v_pk_mul_f32 v[42:43], v[72:73], v[44:45]
	v_pk_mul_f32 v[44:45], v[70:71], v[82:83]
	s_waitcnt vmcnt(4)
	v_pk_mul_f32 v[46:47], v[80:81], v[48:49]
	v_pk_mul_f32 v[48:49], v[78:79], v[84:85]
	v_pk_mul_f32 v[50:51], v[76:77], v[52:53]
	v_pk_mul_f32 v[52:53], v[74:75], v[86:87]
	v_mov_b32_e32 v54, v64
	.p2align	8

.LBB0_206:
	s_or_b64 exec, exec, s[4:5]
	v_and_b32_e32 v4, 0xffffffc0, v140
	v_ashrrev_i32_e32 v5, 31, v4
	v_lshlrev_b32_e32 v7, 1, v141
	v_lshlrev_b64 v[4:5], 11, v[4:5]
	v_lshlrev_b32_e32 v6, 1, v139
	v_and_b32_e32 v7, 0x400, v7
	v_lshlrev_b32_e64 v21, v27, 2
	v_or3_b32 v4, v7, v6, v4
	v_lshl_add_u64 v[4:5], s[88:89], 0, v[4:5]
	v_and_b32_e32 v22, 0x1fc0, v140
	s_mov_b32 s4, 0
	v_sub_u32_e32 v23, 0, v21
	s_mov_b64 s[10:11], 0
	.p2align	8

.LBB0_379:
	s_andn2_b64 vcc, exec, s[2:3]
	s_cbranch_vccnz .LBB0_421
	v_readlane_b32 s4, v246, 28
	v_lshlrev_b32_e32 v54, 5, v49
	v_mov_b32_e32 v55, v149
	v_readlane_b32 s5, v246, 29
	v_cmp_eq_u32_e64 s[38:39], 0, v49
	v_ashrrev_i32_e32 v49, 8, v48
	v_lshl_add_u64 v[84:85], s[4:5], 0, v[54:55]
	v_lshrrev_b32_e32 v54, 5, v48
	v_and_b32_e32 v58, 6, v54
	v_lshlrev_b32_e32 v54, 7, v49
	v_readlane_b32 s4, v246, 41
	v_ashrrev_i32_e32 v55, 31, v54
	v_readlane_b32 s5, v246, 42
	v_bfe_u32 v56, v48, 1, 5
	v_and_b32_e32 v56, 24, v56
	v_lshl_add_u64 v[54:55], v[54:55], 1, s[4:5]
	v_mov_b32_e32 v57, v149
	v_lshl_add_u64 v[86:87], v[54:55], 0, v[56:57]
	v_bfe_u32 v54, v48, 2, 2
	v_or_b32_e32 v65, v56, v54
	v_and_b32_e32 v53, 63, v48
	v_and_b32_e32 v57, 12, v48
	v_lshlrev_b32_e32 v81, 8, v65
	v_lshrrev_b32_e32 v65, 3, v48
	v_bfe_u32 v55, v53, 1, 1
	v_lshlrev_b32_e32 v62, 1, v58
	v_and_or_b32 v83, v65, 2, v57
	v_or_b32_e32 v65, 4, v56
	v_or_b32_e32 v63, v62, v55
	v_bfe_u32 v110, v65, 2, 2
	v_lshlrev_b32_e32 v59, 3, v48
	v_or_b32_e32 v67, v65, v54
	v_bitop3_b32 v65, v110, v63, v57 bitop3:0x36
	v_lshlrev_b32_e32 v49, 15, v49
	v_and_b32_e32 v59, 8, v59
	v_lshlrev_b32_e32 v111, 4, v65
	v_or_b32_e32 v65, 36, v56
	v_add_u32_e32 v60, v59, v49
	v_lshlrev_b32_e32 v88, 4, v58
	v_lshlrev_b32_e32 v109, 8, v67
	v_or_b32_e32 v67, v65, v54
	v_bfe_u32 v114, v65, 2, 2
	v_or_b32_e32 v58, 1, v58
	v_bitop3_b32 v62, v62, v83, v55 bitop3:0x36
	v_bitop3_b32 v65, v114, v63, v57 bitop3:0x36
	v_lshl_add_u32 v115, v67, 8, v60
	v_lshlrev_b32_e32 v106, 4, v58
	v_lshlrev_b32_e32 v58, 1, v58
	v_add_u32_e32 v49, 0, v49
	v_lshlrev_b32_e32 v62, 4, v62
	v_add_u32_e32 v108, v60, v81
	v_lshl_add_u32 v140, v65, 4, v115
	v_or_b32_e32 v65, 0x44, v56
	v_or_b32_e32 v56, 0x64, v56
	v_or_b32_e32 v120, v58, v55
	v_bitop3_b32 v55, v58, v83, v55 bitop3:0x36
	v_or_b32_e32 v49, v49, v59
	s_add_i32 s3, 0, 0x10000
	v_lshlrev_b32_e32 v51, 11, v51
	v_add_u32_e32 v113, 0x2000, v108
	v_add_u32_e32 v116, 0x4000, v108
	v_or_b32_e32 v67, v65, v54
	v_bfe_u32 v117, v65, 2, 2
	v_add_u32_e32 v119, 0x6000, v108
	v_or_b32_e32 v54, v56, v54
	v_bfe_u32 v56, v56, 2, 2
	v_lshlrev_b32_e32 v55, 4, v55
	v_add3_u32 v167, v81, v49, v62
	v_add3_u32 v168, v109, v49, v111
	v_lshlrev_b32_e32 v49, 2, v80
	v_and_b32_e32 v51, 0x8000, v51
	v_bitop3_b32 v65, v117, v63, v57 bitop3:0x36
	v_bitop3_b32 v63, v56, v63, v57 bitop3:0x36
	v_add_u32_e32 v159, v55, v108
	v_add_u32_e32 v161, v55, v113
	v_add_u32_e32 v163, v55, v116
	v_add_u32_e32 v165, v55, v119
	v_bitop3_b32 v55, v56, v120, v57 bitop3:0x36
	v_add_u32_e32 v169, s3, v49
	v_and_b32_e32 v49, 12, v49
	v_bfe_u32 v56, v80, 2, 2
	v_add_u32_e32 v51, 0, v51
	v_add_u32_e32 v112, v109, v60
	v_bitop3_b32 v58, v110, v120, v57 bitop3:0x36
	v_bitop3_b32 v49, v49, v107, v56 bitop3:0x36
	v_lshl_add_u32 v54, v54, 8, v60
	v_lshl_add_u32 v160, v58, 4, v112
	v_bitop3_b32 v58, v114, v120, v57 bitop3:0x36
	v_ashrrev_i32_e32 v81, 31, v80
	v_lshl_add_u32 v59, v49, 4, v51
	v_lshlrev_b32_e32 v49, 2, v82
	v_ashrrev_i32_e32 v83, 31, v82
	v_lshl_add_u32 v158, v63, 4, v54
	v_lshl_add_u32 v162, v58, 4, v115
	v_bitop3_b32 v58, v117, v120, v57 bitop3:0x36
	v_lshl_add_u32 v166, v55, 4, v54
	v_lshlrev_b64 v[54:55], 13, v[80:81]
	v_add_u32_e32 v81, s3, v49
	v_lshlrev_b64 v[56:57], 13, v[82:83]
	v_and_b32_e32 v49, 12, v49
	v_bfe_u32 v83, v82, 2, 2
	v_bitop3_b32 v49, v49, v107, v83 bitop3:0x36
	v_add_u32_e32 v139, v113, v62
	v_lshl_add_u32 v113, v49, 4, v51
	v_add_u32_e32 v49, 0x400, v48
	v_ashrrev_i32_e32 v83, 5, v49
	v_lshlrev_b32_e32 v49, 2, v83
	v_add_u32_e32 v137, v62, v108
	v_add_u32_e32 v170, s3, v49
	v_and_b32_e32 v49, 12, v49
	v_bfe_u32 v108, v83, 2, 2
	v_bitop3_b32 v49, v49, v107, v108 bitop3:0x36
	v_lshl_add_u32 v115, v49, 4, v51
	v_add_u32_e32 v49, 0x600, v48
	v_ashrrev_i32_e32 v171, 5, v49
	v_lshlrev_b32_e32 v49, 2, v171
	v_add_u32_e32 v172, s3, v49
	v_and_b32_e32 v49, 12, v49
	v_bfe_u32 v108, v171, 2, 2
	v_bitop3_b32 v49, v49, v107, v108 bitop3:0x36
	v_lshl_add_u32 v117, v49, 4, v51
	v_add_u32_e32 v49, 0x800, v48
	v_ashrrev_i32_e32 v173, 5, v49
	v_lshlrev_b32_e32 v49, 2, v173
	v_add_u32_e32 v174, s3, v49
	v_and_b32_e32 v49, 12, v49
	v_bfe_u32 v108, v173, 2, 2
	v_bitop3_b32 v49, v49, v107, v108 bitop3:0x36
	v_add_u32_e32 v143, v119, v62
	v_lshl_add_u32 v119, v49, 4, v51
	v_add_u32_e32 v49, 0xa00, v48
	v_ashrrev_i32_e32 v175, 5, v49
	v_lshlrev_b32_e32 v49, 2, v175
	v_add_u32_e32 v188, s3, v49
	v_and_b32_e32 v49, 12, v49
	v_bfe_u32 v108, v175, 2, 2
	v_bitop3_b32 v49, v49, v107, v108 bitop3:0x36
	v_lshl_add_u32 v121, v49, 4, v51
	v_add_u32_e32 v49, 0xc00, v48
	v_ashrrev_i32_e32 v189, 5, v49
	v_ashrrev_i32_e32 v135, 4, v48
	v_and_b32_e32 v61, 48, v48
	v_lshlrev_b32_e32 v49, 2, v189
	v_add_u32_e32 v48, 0xe00, v48
	v_add_u32_e32 v190, s3, v49
	v_and_b32_e32 v49, 12, v49
	v_bfe_u32 v108, v189, 2, 2
	v_ashrrev_i32_e32 v191, 5, v48
	v_readlane_b32 s4, v245, 37
	v_bitop3_b32 v49, v49, v107, v108 bitop3:0x36
	v_lshlrev_b32_e32 v48, 2, v191
	v_add_u32_e32 v61, s4, v61
	v_lshl_add_u32 v123, v49, 4, v51
	v_add_u32_e32 v192, s3, v48
	v_and_b32_e32 v48, 12, v48
	v_bfe_u32 v49, v191, 2, 2
	v_readlane_b32 s4, v246, 43
	v_bitop3_b32 v48, v48, v107, v49 bitop3:0x36
	v_readlane_b32 s5, v246, 44
	v_lshl_add_u32 v118, v67, 8, v60
	v_or_b32_e32 v63, 48, v53
	v_or_b32_e32 v53, 0x70, v53
	v_lshl_add_u32 v125, v48, 4, v51
	v_lshl_add_u64 v[48:49], s[4:5], 0, v[54:55]
	v_lshlrev_b32_e32 v50, 2, v50
	v_mov_b32_e32 v51, v149
	s_and_b32 s2, s10, -2
	v_lshl_add_u32 v134, v89, 2, s3
	v_lshlrev_b32_e32 v52, 7, v107
	v_lshl_add_u32 v136, v135, 2, s3
	s_lshl_b32 s20, s0, 4
	v_add_u32_e32 v141, v116, v62
	v_lshl_add_u32 v142, v65, 4, v118
	v_mul_u32_u24_e32 v60, 0x110, v107
	v_mul_u32_u24_e32 v63, 0x110, v63
	v_mul_u32_u24_e32 v53, 0x110, v53
	v_lshl_add_u32 v164, v58, 4, v118
	v_lshlrev_b32_e32 v58, 8, v80
	v_lshlrev_b32_e32 v62, 8, v82
	v_lshlrev_b32_e32 v114, 8, v83
	v_lshlrev_b32_e32 v116, 8, v171
	v_lshlrev_b32_e32 v118, 8, v173
	v_lshlrev_b32_e32 v120, 8, v175
	v_lshlrev_b32_e32 v122, 8, v189
	v_lshlrev_b32_e32 v124, 8, v191
	v_lshl_add_u64 v[108:109], v[48:49], 0, v[50:51]
	v_lshl_add_u64 v[48:49], s[4:5], 0, v[56:57]
	s_lshl_b32 s3, s10, 1
	s_lshr_b32 s14, s10, 1
	s_mov_b32 s15, 0
	v_cmp_eq_u32_e64 s[40:41], 0, v107
	s_addk_i32 s20, 0xfe00
	v_add_u32_e32 v138, v111, v112
	s_waitcnt vmcnt(9)
	v_mov_b32_e32 v65, v64
	v_mov_b32_e32 v90, v64
	v_mov_b32_e32 v91, v64
	s_waitcnt vmcnt(8)
	v_mov_b32_e32 v67, v66
	v_mov_b32_e32 v92, v66
	v_mov_b32_e32 v93, v66
	s_waitcnt vmcnt(7)
	v_mov_b32_e32 v69, v68
	v_mov_b32_e32 v94, v68
	v_mov_b32_e32 v95, v68
	s_waitcnt vmcnt(6)
	v_mov_b32_e32 v71, v70
	v_mov_b32_e32 v96, v70
	v_mov_b32_e32 v97, v70
	s_waitcnt vmcnt(5)
	v_mov_b32_e32 v73, v72
	v_mov_b32_e32 v98, v72
	v_mov_b32_e32 v99, v72
	s_waitcnt vmcnt(4)
	v_mov_b32_e32 v75, v74
	v_mov_b32_e32 v100, v74
	v_mov_b32_e32 v101, v74
	s_waitcnt vmcnt(3)
	v_mov_b32_e32 v77, v76
	v_mov_b32_e32 v102, v76
	v_mov_b32_e32 v103, v76
	s_waitcnt vmcnt(2)
	v_mov_b32_e32 v79, v78
	v_mov_b32_e32 v104, v78
	v_mov_b32_e32 v105, v78
	v_lshl_add_u64 v[110:111], v[48:49], 0, v[50:51]
	s_add_i32 s21, s3, -2
	s_add_i32 s22, s2, -1
	v_lshlrev_b32_e32 v112, 1, v52
	v_add_u32_e32 v193, v59, v58
	v_add_u32_e32 v194, v113, v62
	v_add_u32_e32 v195, v115, v114
	v_add_u32_e32 v196, v117, v116
	v_add_u32_e32 v197, v119, v118
	v_add_u32_e32 v198, v121, v120
	v_add_u32_e32 v199, v123, v122
	v_add_u32_e32 v200, v125, v124
	v_add_u32_e32 v201, v61, v63
	v_add_u32_e32 v202, v61, v53
	v_add_u32_e32 v203, v61, v60
	s_waitcnt vmcnt(0)
	s_branch .LBB0_382
.LBB0_381:
	s_add_i32 s21, s21, -2
	s_add_i32 s22, s22, -2
	s_cmp_lg_u32 s11, s15
	s_barrier
	s_cbranch_scc0 .LBB0_421
	.p2align	8

.LBB0_388:
	s_andn2_b64 vcc, exec, s[8:9]
	s_cbranch_vccnz .LBB0_392
	s_waitcnt vmcnt(8)
	v_add_f32_e32 v48, v44, v45
	s_waitcnt lgkmcnt(0)
	v_add_f32_e32 v49, v46, v47
	v_add_f32_e32 v48, v48, v49
	s_waitcnt vmcnt(8)
	v_add_f32_e32 v49, v36, v37
	v_add_f32_e32 v50, v38, v39
	v_add_f32_e32 v49, v49, v50
	v_and_b32_e32 v50, 64, v181
	v_add_f32_e32 v48, v48, v49
	v_xor_b32_e32 v49, 1, v181
	v_add_u32_e32 v50, 64, v50
	v_cmp_lt_i32_e32 vcc, v49, v50
	s_nop 1
	v_cndmask_b32_e32 v49, v181, v49, vcc
	v_lshlrev_b32_e32 v49, 2, v49
	ds_bpermute_b32 v49, v49, v48
	s_waitcnt lgkmcnt(0)
	v_add_f32_e32 v48, v48, v49
	v_xor_b32_e32 v49, 2, v181
	v_cmp_lt_i32_e32 vcc, v49, v50
	s_nop 1
	v_cndmask_b32_e32 v49, v181, v49, vcc
	v_lshlrev_b32_e32 v49, 2, v49
	ds_bpermute_b32 v49, v49, v48
	s_and_saveexec_b64 s[8:9], s[38:39]
	s_cbranch_execz .LBB0_391
	s_waitcnt lgkmcnt(0)
	v_add_f32_e32 v48, v48, v49
	v_fmamk_f32 v48, v48, 0x3a000000, v178
	v_mul_f32_e32 v49, 0x4b800000, v48
	v_cmp_gt_f32_e32 vcc, s62, v48
	s_nop 1
	v_cndmask_b32_e32 v48, v48, v49, vcc
	v_rsq_f32_e32 v48, v48
	s_nop 0
	v_mul_f32_e32 v49, 0x45800000, v48
	v_cndmask_b32_e32 v48, v48, v49, vcc
	ds_write_b32 v134, v48

.LBB0_392:
	s_waitcnt lgkmcnt(0)
	s_barrier
	ds_read_b32 v54, v169
	s_add_i32 s8, s20, s23
	s_waitcnt vmcnt(8)
	v_lshlrev_b32_e32 v48, 16, v12
	v_and_b32_e32 v49, 0xffff0000, v12
	v_lshlrev_b32_e32 v50, 16, v13
	v_and_b32_e32 v51, 0xffff0000, v13
	v_lshlrev_b32_e32 v52, 16, v14
	v_and_b32_e32 v53, 0xffff0000, v14
	v_lshlrev_b32_e32 v56, 16, v15
	v_and_b32_e32 v57, 0xffff0000, v15
	s_ashr_i32 s9, s8, 31
	s_waitcnt lgkmcnt(0)
	v_pk_mul_f32 v[48:49], v[54:55], v[48:49] op_sel_hi:[0,1]
	v_pk_mul_f32 v[50:51], v[54:55], v[50:51] op_sel_hi:[0,1]
	v_pk_mul_f32 v[52:53], v[54:55], v[52:53] op_sel_hi:[0,1]
	v_pk_mul_f32 v[54:55], v[54:55], v[56:57] op_sel_hi:[0,1]
	v_cndmask_b32_e64 v56, 0, 1, s[4:5]
	s_lshl_b64 s[8:9], s[8:9], 18
	s_waitcnt vmcnt(8)
	v_pk_mul_f32 v[48:49], v[4:5], v[48:49]
	v_pk_mul_f32 v[50:51], v[6:7], v[50:51]
	v_pk_mul_f32 v[52:53], v[0:1], v[52:53]
	v_cmp_ne_u32_e64 s[42:43], 1, v56
	s_andn2_b64 vcc, exec, s[4:5]
	v_pk_mul_f32 v[54:55], v[2:3], v[54:55]
	s_cbranch_vccnz .LBB0_394
	v_lshl_add_u64 v[56:57], v[108:109], 0, s[8:9]
	global_store_dwordx4 v[56:57], v[48:51], off
	global_store_dwordx4 v[56:57], v[52:55], off offset:16

.LBB0_505:
	s_ashr_i32 s11, s3, 31
	s_lshr_b32 s11, s11, 27
	s_add_i32 s11, s3, s11
	s_ashr_i32 s20, s11, 5
	s_lshl_b32 s11, s20, 6
	s_lshl_b32 s21, s20, 10
	s_lshl_b32 s20, s3, 5
	s_sub_i32 s20, s20, s21
	s_ashr_i32 s39, s20, 8
	s_mul_i32 s40, s39, s73
	s_ashr_i32 s41, s40, 31
	v_add_u32_e32 v2, s11, v61
	s_lshl_b64 s[40:41], s[40:41], 1
	v_ashrrev_i32_e32 v3, 31, v2
	v_mov_b64_e32 v[0:1], s[40:41]
	v_mad_u64_u32 v[0:1], s[40:41], s4, v2, v[0:1]
	v_mul_lo_u32 v3, s4, v3
	v_mul_lo_u32 v2, s5, v2
	v_add3_u32 v1, v2, v1, v3
	v_lshl_add_u64 v[48:49], v[36:37], 0, v[0:1]
	v_lshl_add_u64 v[50:51], v[38:39], 0, v[0:1]
	v_lshl_add_u64 v[52:53], v[40:41], 0, v[0:1]
	v_lshl_add_u64 v[54:55], v[42:43], 0, v[0:1]
	v_subrev_u32_e32 v0, s21, v62
	v_ashrrev_i32_e32 v1, 31, v0
	v_mad_u64_u32 v[56:57], s[40:41], s8, v0, v[44:45]
	v_mul_lo_u32 v1, s8, v1
	v_mul_lo_u32 v2, s9, v0
	v_mad_u64_u32 v[58:59], s[40:41], s8, v0, v[46:47]
	v_mov_b32_e32 v0, 0
	v_add3_u32 v57, v2, v57, v1
	v_add3_u32 v59, v2, v59, v1
	s_mov_b32 s21, 0
	v_mov_b32_e32 v1, v0
	v_mov_b32_e32 v2, v0
	v_mov_b32_e32 v3, v0
	v_mov_b32_e32 v4, v0
	v_mov_b32_e32 v5, v0
	v_mov_b32_e32 v6, v0
	v_mov_b32_e32 v7, v0
	v_mov_b32_e32 v8, v0
	v_mov_b32_e32 v9, v0
	v_mov_b32_e32 v10, v0
	v_mov_b32_e32 v11, v0
	v_mov_b32_e32 v12, v0
	v_mov_b32_e32 v13, v0
	v_mov_b32_e32 v14, v0
	v_mov_b32_e32 v15, v0
	v_mov_b32_e32 v16, v0
	v_mov_b32_e32 v17, v0
	v_mov_b32_e32 v18, v0
	v_mov_b32_e32 v19, v0
	v_mov_b32_e32 v20, v0
	v_mov_b32_e32 v21, v0
	v_mov_b32_e32 v22, v0
	v_mov_b32_e32 v23, v0
	v_mov_b32_e32 v24, v0
	v_mov_b32_e32 v25, v0
	v_mov_b32_e32 v26, v0
	v_mov_b32_e32 v27, v0
	v_mov_b32_e32 v28, v0
	v_mov_b32_e32 v29, v0
	v_mov_b32_e32 v30, v0
	v_mov_b32_e32 v31, v0
	s_and_b32 vcc_lo, s38, 0x7f
	s_cbranch_scc1 .Lsgp_orig
	v_lshl_add_u64 v[224:225], v[48:49], 0, v[34:35]
	v_lshl_add_u64 v[226:227], v[50:51], 0, v[34:35]
	v_lshl_add_u64 v[228:229], v[52:53], 0, v[34:35]
	v_lshl_add_u64 v[230:231], v[54:55], 0, v[34:35]
	v_lshl_add_u64 v[232:233], v[56:57], 0, v[34:35]
	v_lshl_add_u64 v[234:235], v[58:59], 0, v[34:35]
	global_load_dwordx4 v[66:69], v[232:233], off
	global_load_dwordx4 v[74:77], v[224:225], off
	global_load_dwordx4 v[70:73], v[234:235], off
	global_load_dwordx4 v[78:81], v[226:227], off
	global_load_dwordx4 v[82:85], v[228:229], off
	global_load_dwordx4 v[86:89], v[230:231], off
	global_load_dwordx4 v[90:93], v[232:233], off offset:64
	global_load_dwordx4 v[98:101], v[224:225], off offset:64
	global_load_dwordx4 v[94:97], v[234:235], off offset:64
	global_load_dwordx4 v[102:105], v[226:227], off offset:64
	global_load_dwordx4 v[106:109], v[228:229], off offset:64
	global_load_dwordx4 v[110:113], v[230:231], off offset:64
	global_load_dwordx4 v[114:117], v[232:233], off offset:128
	global_load_dwordx4 v[122:125], v[224:225], off offset:128
	global_load_dwordx4 v[118:121], v[234:235], off offset:128
	global_load_dwordx4 v[188:191], v[226:227], off offset:128
	global_load_dwordx4 v[192:195], v[228:229], off offset:128
	global_load_dwordx4 v[196:199], v[230:231], off offset:128
	global_load_dwordx4 v[200:203], v[232:233], off offset:192
	global_load_dwordx4 v[208:211], v[224:225], off offset:192
	global_load_dwordx4 v[204:207], v[234:235], off offset:192
	global_load_dwordx4 v[212:215], v[226:227], off offset:192
	global_load_dwordx4 v[216:219], v[228:229], off offset:192
	global_load_dwordx4 v[220:223], v[230:231], off offset:192
	s_movk_i32 s21, 0x80
	.p2align	8

.LBB0_599:
	s_add_i32 s75, s75, 4
	s_cmp_lt_u32 s78, 28
	s_cbranch_scc0 .LBB0_588
	.p2align	8
